# v42 plus zeroed never-stored DFT matrix rows (k>2048): lower MFMA operand toggling on 12 of 108 DFT units
# speedup vs baseline: 1.0005x; 1.0005x over previous
; DI u32x4 pack8(const float* v) { u32x4 w; w.x = pk2(v[0], v[1]); w.y = pk2(v[2], v[3]); w.z = pk2(v[4], v[5]); w.w = pk2(v[6], v[7]); return w; }
; DI void sincos_rev(float rev, float& s, float& c) { const float f = rev - floorf(rev); s = __builtin_amdgcn_sinf(f); c = __builtin_amdgcn_cosf(f); }
; DI void phase_prep(const Params& P, int layer, int gtid, int nthr) {
;     ...
;         for (int idx = gtid; idx < DFTM * 512; idx += nthr) {
;             const int r = idx >> 9, l0 = (idx & 511) * 8, type = r >= DFTR, k = r - type * DFTR; float v[8];
; #pragma unroll
;             for (int j = 0; j < 8; ++j) { float s, co; sincos_rev((float)((k * (l0 + j)) & 4095) * (1.0f / 4096.0f), s, co); v[j] = (type ? s : co) * (1.0f / 64.0f); }
;             *(u32x4*)(dft + (size_t)r * 4096 + l0) = pack8(v);
;         }
.LBB0_315:
	v_ashrrev_i32_e32 v4, 9, v3
	v_cmp_lt_i32_e64 s[14:15], s88, v4
	v_and_b32_e32 v6, 0xff8, v1
	v_ashrrev_i32_e32 v5, 31, v4
	v_cndmask_b32_e64 v8, 0, v250, s[14:15]
	v_lshlrev_b32_e32 v188, 1, v6
	v_lshlrev_b64 v[6:7], 13, v[4:5]
	v_add_u32_e32 v10, v8, v4
	v_and_b32_e32 v100, 0xfff, v10
	v_cmp_gt_i32_e32 vcc, 0x801, v100
	v_mov_b32_e32 v100, 0x3c800000
	v_cndmask_b32_e32 v100, 0, v100, vcc
	v_lshl_add_u64 v[4:5], s[8:9], 0, v[6:7]
	v_mul_lo_u32 v6, v10, v1
	v_lshl_add_u64 v[8:9], v[4:5], 0, v[188:189]
	v_and_b32_e32 v4, 0xff8, v6
	v_add_u32_e32 v5, v6, v10
	v_cvt_f32_u32_e32 v4, v4
	v_and_b32_e32 v6, 0xfff, v5
	v_add_u32_e32 v5, v5, v10
	v_cvt_f32_u32_e32 v6, v6
	v_and_b32_e32 v7, 0xffe, v5
	v_add_u32_e32 v5, v5, v10
	v_cvt_f32_u32_e32 v7, v7
	v_and_b32_e32 v11, 0xfff, v5
	v_add_u32_e32 v5, v5, v10
	v_cvt_f32_u32_e32 v11, v11
	v_and_b32_e32 v12, 0xffc, v5
	v_add_u32_e32 v5, v5, v10
	v_mul_f32_e32 v13, 0x39800000, v4
	v_cvt_f32_u32_e32 v12, v12
	v_and_b32_e32 v14, 0xfff, v5
	v_add_u32_e32 v5, v5, v10
	v_floor_f32_e32 v13, v13
	v_mul_f32_e32 v15, 0x39800000, v6
	v_cvt_f32_u32_e32 v14, v14
	v_and_b32_e32 v16, 0xffe, v5
	v_add_u32_e32 v5, v5, v10
	v_fma_f32 v4, v4, s60, -v13
	v_floor_f32_e32 v10, v15
	v_mul_f32_e32 v13, 0x39800000, v7
	v_and_b32_e32 v5, 0xfff, v5
	v_cvt_f32_u32_e32 v15, v16
	v_fma_f32 v6, v6, s60, -v10
	v_floor_f32_e32 v10, v13
	v_mul_f32_e32 v13, 0x39800000, v11
	v_cvt_f32_u32_e32 v5, v5
	v_fma_f32 v7, v7, s60, -v10
	v_floor_f32_e32 v10, v13
	v_mul_f32_e32 v13, 0x39800000, v12
	v_sin_f32_e32 v16, v4
	v_cos_f32_e32 v4, v4
	v_sin_f32_e32 v17, v6
	v_cos_f32_e32 v6, v6
	v_fma_f32 v10, v11, s60, -v10
	v_floor_f32_e32 v11, v13
	v_mul_f32_e32 v13, 0x39800000, v14
	v_sin_f32_e32 v18, v7
	v_cos_f32_e32 v7, v7
	v_fma_f32 v11, v12, s60, -v11
	v_floor_f32_e32 v12, v13
	v_mul_f32_e32 v13, 0x39800000, v15
	v_fma_f32 v12, v14, s60, -v12
	v_mul_f32_e32 v14, 0x39800000, v5
	v_sin_f32_e32 v19, v10
	v_cos_f32_e32 v10, v10
	v_floor_f32_e32 v13, v13
	v_floor_f32_e32 v14, v14
	v_cndmask_b32_e64 v4, v4, v16, s[14:15]
	v_sin_f32_e32 v16, v11
	v_cos_f32_e32 v11, v11
	v_cndmask_b32_e64 v6, v6, v17, s[14:15]
	v_sin_f32_e32 v17, v12
	v_cos_f32_e32 v12, v12
	v_fma_f32 v13, v15, s60, -v13
	v_fma_f32 v5, v5, s60, -v14
	v_cndmask_b32_e64 v7, v7, v18, s[14:15]
	v_sin_f32_e32 v15, v13
	v_cos_f32_e32 v13, v13
	v_sin_f32_e32 v14, v5
	v_cos_f32_e32 v18, v5
	v_mul_f32_e32 v4, v100, v4
	v_mul_f32_e32 v6, v100, v6
	v_cndmask_b32_e64 v10, v10, v19, s[14:15]
	v_mul_f32_e32 v7, v100, v7
	v_cvt_pk_bf16_f32 v4, v4, v6
	v_mul_f32_e32 v5, v100, v10
	v_cndmask_b32_e64 v6, v11, v16, s[14:15]
	v_cndmask_b32_e64 v10, v12, v17, s[14:15]
	v_add_u32_e32 v3, s84, v3
	s_mov_b32 s2, 0x23ffff
	v_mul_f32_e32 v6, v100, v6
	v_cvt_pk_bf16_f32 v5, v7, v5
	v_mul_f32_e32 v7, v100, v10
	v_cndmask_b32_e64 v10, v13, v15, s[14:15]
	v_cndmask_b32_e64 v11, v18, v14, s[14:15]
	v_cmp_lt_i32_e32 vcc, s2, v3
	v_mul_f32_e32 v10, v100, v10
	v_cvt_pk_bf16_f32 v6, v6, v7
	v_mul_f32_e32 v7, v100, v11
	s_or_b64 s[16:17], vcc, s[16:17]
	v_add_u32_e32 v1, s19, v1
	v_cvt_pk_bf16_f32 v7, v10, v7
	global_store_dwordx4 v[8:9], v[4:7], off
	s_andn2_b64 exec, exec, s[16:17]
	s_cbranch_execnz .LBB0_315
